# MLA attention: waves 4-7 skewed by one barrier, 2 barriers per key tile, K tile LDS write moved to the top of the next iteration
# speedup vs baseline: 1.0203x; 1.0203x over previous
.LBB0_813:
	s_barrier
	v_sub_f32_e32 v66, v66, v98
	v_exp_f32_e32 v99, v66
	v_sub_f32_e32 v66, v67, v98
	v_exp_f32_e32 v100, v66
	v_sub_f32_e32 v66, v68, v98
	v_exp_f32_e32 v101, v66
	v_sub_f32_e32 v66, v69, v98
	v_exp_f32_e32 v102, v66
	v_sub_f32_e32 v66, v70, v98
	v_exp_f32_e32 v103, v66
	v_sub_f32_e32 v66, v71, v98
	v_exp_f32_e32 v104, v66
	v_sub_f32_e32 v66, v72, v98
	v_exp_f32_e32 v105, v66
	v_sub_f32_e32 v66, v73, v98
	v_exp_f32_e32 v106, v66
	v_sub_f32_e32 v66, v74, v98
	v_exp_f32_e32 v74, v66
	v_sub_f32_e32 v66, v75, v98
	v_exp_f32_e32 v75, v66
	v_sub_f32_e32 v66, v76, v98
	v_exp_f32_e32 v76, v66
	v_sub_f32_e32 v66, v77, v98
	v_exp_f32_e32 v77, v66
	v_sub_f32_e32 v66, v78, v98
	v_exp_f32_e32 v78, v66
	v_sub_f32_e32 v66, v79, v98
	v_exp_f32_e32 v79, v66
	v_sub_f32_e32 v66, v80, v98
	v_add3_u32 v70, s0, v189, v205
	v_exp_f32_e32 v80, v66
	v_sub_f32_e32 v66, v81, v98
	v_add_u32_e32 v109, 0x6800, v70
	v_exp_f32_e32 v81, v66
	ds_read2_b64 v[66:69], v109 offset1:2
	v_sub_f32_e32 v82, v82, v98
	v_sub_f32_e32 v83, v83, v98
	v_sub_f32_e32 v84, v84, v98
	v_sub_f32_e32 v85, v85, v98
	v_sub_f32_e32 v86, v86, v98
	v_sub_f32_e32 v87, v87, v98
	v_sub_f32_e32 v88, v88, v98
	v_sub_f32_e32 v89, v89, v98
	v_add_u32_e32 v112, 0x8800, v70
	v_exp_f32_e32 v82, v82
	v_exp_f32_e32 v83, v83
	v_exp_f32_e32 v84, v84
	v_exp_f32_e32 v85, v85
	v_exp_f32_e32 v86, v86
	v_exp_f32_e32 v87, v87
	v_exp_f32_e32 v88, v88
	v_exp_f32_e32 v89, v89
	ds_read2_b64 v[70:73], v112 offset0:32 offset1:34
	v_sub_f32_e32 v50, v50, v98
	v_exp_f32_e32 v107, v50
	v_sub_f32_e32 v50, v51, v98
	v_exp_f32_e32 v108, v50
	v_sub_f32_e32 v50, v52, v98
	v_exp_f32_e32 v110, v50
	v_sub_f32_e32 v111, v53, v98
	v_cvt_pk_bf16_f32 v50, v82, v83
	v_cvt_pk_bf16_f32 v51, v84, v85
	v_cvt_pk_bf16_f32 v52, v86, v87
	v_cvt_pk_bf16_f32 v53, v88, v89
	v_sub_f32_e32 v54, v54, v98
	v_exp_f32_e32 v113, v54
	s_waitcnt lgkmcnt(1)
	v_mfma_f32_32x32x16_bf16 v[18:33], v[66:69], v[50:53], v[18:33]
	ds_read2_b64 v[66:69], v109 offset0:4 offset1:6
	v_sub_f32_e32 v54, v55, v98
	v_sub_f32_e32 v90, v90, v98
	v_sub_f32_e32 v91, v91, v98
	v_sub_f32_e32 v92, v92, v98
	v_sub_f32_e32 v93, v93, v98
	v_sub_f32_e32 v94, v94, v98
	v_sub_f32_e32 v95, v95, v98
	v_sub_f32_e32 v96, v96, v98
	v_sub_f32_e32 v97, v97, v98
	v_exp_f32_e32 v114, v54
	v_sub_f32_e32 v54, v56, v98
	v_exp_f32_e32 v90, v90
	v_exp_f32_e32 v91, v91
	v_exp_f32_e32 v92, v92
	v_exp_f32_e32 v93, v93
	v_exp_f32_e32 v94, v94
	v_exp_f32_e32 v95, v95
	v_exp_f32_e32 v96, v96
	v_exp_f32_e32 v97, v97
	s_waitcnt lgkmcnt(1)
	v_mfma_f32_32x32x16_bf16 v[2:17], v[70:73], v[50:53], v[2:17]
	v_exp_f32_e32 v70, v54
	v_sub_f32_e32 v71, v57, v98
	ds_read2_b64 v[54:57], v112 offset0:36 offset1:38
	v_cvt_pk_bf16_f32 v50, v90, v91
	v_cvt_pk_bf16_f32 v51, v92, v93
	v_cvt_pk_bf16_f32 v52, v94, v95
	v_cvt_pk_bf16_f32 v53, v96, v97
	v_sub_f32_e32 v58, v58, v98
	v_exp_f32_e32 v72, v58
	s_waitcnt lgkmcnt(1)
	v_mfma_f32_32x32x16_bf16 v[18:33], v[66:69], v[50:53], v[18:33]
	ds_read2_b64 v[66:69], v109 offset0:8 offset1:10
	v_sub_f32_e32 v58, v59, v98
	v_exp_f32_e32 v73, v58
	v_sub_f32_e32 v58, v60, v98
	v_exp_f32_e32 v115, v58
	v_sub_f32_e32 v58, v61, v98
	v_exp_f32_e32 v111, v111
	s_waitcnt lgkmcnt(1)
	v_mfma_f32_32x32x16_bf16 v[2:17], v[54:57], v[50:53], v[2:17]
	ds_read2_b64 v[54:57], v112 offset0:40 offset1:42
	v_cvt_pk_bf16_f32 v50, v99, v100
	v_cvt_pk_bf16_f32 v51, v101, v102
	v_cvt_pk_bf16_f32 v52, v103, v104
	v_cvt_pk_bf16_f32 v53, v105, v106
	v_exp_f32_e32 v71, v71
	v_sub_f32_e32 v34, v34, v98
	s_waitcnt lgkmcnt(1)
	v_mfma_f32_32x32x16_bf16 v[18:33], v[66:69], v[50:53], v[18:33]
	v_exp_f32_e32 v66, v58
	v_sub_f32_e32 v58, v62, v98
	v_exp_f32_e32 v62, v58
	v_sub_f32_e32 v58, v63, v98
	v_exp_f32_e32 v63, v58
	ds_read2_b64 v[58:61], v109 offset0:12 offset1:14
	v_exp_f32_e32 v67, v34
	s_waitcnt lgkmcnt(1)
	v_mfma_f32_32x32x16_bf16 v[2:17], v[54:57], v[50:53], v[2:17]
	ds_read2_b64 v[54:57], v112 offset0:44 offset1:46
	v_cvt_pk_bf16_f32 v50, v74, v75
	v_cvt_pk_bf16_f32 v51, v76, v77
	v_cvt_pk_bf16_f32 v52, v78, v79
	v_cvt_pk_bf16_f32 v53, v80, v81
	v_sub_f32_e32 v34, v35, v98
	v_exp_f32_e32 v68, v34
	s_waitcnt lgkmcnt(1)
	v_mfma_f32_32x32x16_bf16 v[18:33], v[58:61], v[50:53], v[18:33]
	ds_read2_b64 v[58:61], v109 offset0:16 offset1:18
	v_sub_f32_e32 v34, v36, v98
	v_exp_f32_e32 v69, v34
	v_cvt_pk_bf16_f32 v34, v107, v108
	v_cvt_pk_bf16_f32 v35, v110, v111
	v_cvt_pk_bf16_f32 v36, v113, v114
	v_sub_f32_e32 v38, v38, v98
	s_waitcnt lgkmcnt(1)
	v_mfma_f32_32x32x16_bf16 v[2:17], v[54:57], v[50:53], v[2:17]
	ds_read2_b64 v[50:53], v112 offset0:48 offset1:50
	v_sub_f32_e32 v54, v37, v98
	v_cvt_pk_bf16_f32 v37, v70, v71
	v_sub_f32_e32 v64, v64, v98
	v_sub_f32_e32 v65, v65, v98
	v_exp_f32_e32 v64, v64
	v_exp_f32_e32 v65, v65
	s_waitcnt lgkmcnt(1)
	v_mfma_f32_32x32x16_bf16 v[18:33], v[58:61], v[34:37], v[18:33]
	v_exp_f32_e32 v58, v54
	v_exp_f32_e32 v59, v38
	v_sub_f32_e32 v38, v39, v98
	ds_read2_b64 v[54:57], v109 offset0:20 offset1:22
	v_exp_f32_e32 v60, v38
	v_sub_f32_e32 v38, v40, v98
	v_exp_f32_e32 v61, v38
	s_waitcnt lgkmcnt(1)
	v_mfma_f32_32x32x16_bf16 v[2:17], v[50:53], v[34:37], v[2:17]
	v_sub_f32_e32 v50, v41, v98
	ds_read2_b64 v[38:41], v112 offset0:52 offset1:54
	v_cvt_pk_bf16_f32 v34, v72, v73
	v_cvt_pk_bf16_f32 v35, v115, v66
	v_cvt_pk_bf16_f32 v36, v62, v63
	v_cvt_pk_bf16_f32 v37, v64, v65
	v_sub_f32_e32 v42, v42, v98
	v_sub_f32_e32 v48, v48, v98
	s_waitcnt lgkmcnt(1)
	v_mfma_f32_32x32x16_bf16 v[18:33], v[54:57], v[34:37], v[18:33]
	v_exp_f32_e32 v54, v50
	ds_read2_b64 v[50:53], v109 offset0:24 offset1:26
	v_exp_f32_e32 v55, v42
	v_sub_f32_e32 v42, v43, v98
	v_exp_f32_e32 v56, v42
	v_sub_f32_e32 v42, v44, v98
	v_exp_f32_e32 v57, v42
	s_waitcnt lgkmcnt(1)
	v_mfma_f32_32x32x16_bf16 v[2:17], v[38:41], v[34:37], v[2:17]
	ds_read2_b64 v[38:41], v112 offset0:56 offset1:58
	v_sub_f32_e32 v42, v45, v98
	v_cvt_pk_bf16_f32 v34, v67, v68
	v_cvt_pk_bf16_f32 v35, v69, v58
	v_cvt_pk_bf16_f32 v36, v59, v60
	v_cvt_pk_bf16_f32 v37, v61, v54
	v_exp_f32_e32 v48, v48
	s_lshl_b64 s[10:11], s[10:11], 10
	s_waitcnt lgkmcnt(1)
	v_mfma_f32_32x32x16_bf16 v[18:33], v[50:53], v[34:37], v[18:33]
	v_exp_f32_e32 v50, v42
	v_sub_f32_e32 v42, v46, v98
	v_exp_f32_e32 v46, v42
	v_sub_f32_e32 v42, v47, v98
	v_exp_f32_e32 v47, v42
	ds_read2_b64 v[42:45], v109 offset0:28 offset1:30
	s_add_u32 s0, s36, s10
	s_waitcnt lgkmcnt(1)
	v_mfma_f32_32x32x16_bf16 v[2:17], v[38:41], v[34:37], v[2:17]
	ds_read2_b64 v[38:41], v112 offset0:60 offset1:62
	v_sub_f32_e32 v34, v49, v98
	v_exp_f32_e32 v49, v34
	v_cvt_pk_bf16_f32 v34, v55, v56
	v_cvt_pk_bf16_f32 v35, v57, v50
	v_cvt_pk_bf16_f32 v36, v46, v47
	v_cvt_pk_bf16_f32 v37, v48, v49
	s_addc_u32 s11, s37, s11
	s_lshl_b32 s10, s49, 7
	s_waitcnt lgkmcnt(1)
	v_mfma_f32_32x32x16_bf16 v[18:33], v[42:45], v[34:37], v[18:33]
	s_add_u32 s10, s0, s10
	s_addc_u32 s11, s11, 0
	s_waitcnt lgkmcnt(0)
	s_cmpk_lt_i32 s40, 0x100
	s_cbranch_scc0 .Lmla_fin_nobar
	s_barrier
.Lmla_fin_nobar:
	v_mfma_f32_32x32x16_bf16 v[2:17], v[38:41], v[34:37], v[2:17]
	v_add_f32_e32 v34, 0, v82
	v_add_f32_e32 v34, v83, v34
	v_add_f32_e32 v34, v84, v34
	v_add_f32_e32 v34, v85, v34
	v_add_f32_e32 v34, v86, v34
	v_add_f32_e32 v34, v87, v34
	v_add_f32_e32 v34, v88, v34
	v_add_f32_e32 v34, v89, v34
	v_add_f32_e32 v34, v90, v34
	v_add_f32_e32 v34, v91, v34
	v_add_f32_e32 v34, v92, v34
	v_add_f32_e32 v34, v93, v34
	v_add_f32_e32 v34, v94, v34
	v_add_f32_e32 v34, v95, v34
	v_add_f32_e32 v34, v96, v34
	v_add_f32_e32 v34, v97, v34
	v_add_f32_e32 v34, v99, v34
	v_add_f32_e32 v34, v100, v34
	v_add_f32_e32 v34, v101, v34
	v_add_f32_e32 v34, v102, v34
	v_add_f32_e32 v34, v103, v34
	v_add_f32_e32 v34, v104, v34
	v_add_f32_e32 v34, v105, v34
	v_add_f32_e32 v34, v106, v34
	v_add_f32_e32 v34, v74, v34
	v_add_f32_e32 v34, v75, v34
	v_add_f32_e32 v34, v76, v34
	v_add_f32_e32 v34, v77, v34
	v_add_f32_e32 v34, v78, v34
	v_add_f32_e32 v34, v79, v34
	v_add_f32_e32 v34, v80, v34
	v_add_f32_e32 v34, v81, v34
	v_add_f32_e32 v34, v107, v34
	v_add_f32_e32 v34, v108, v34
	v_add_f32_e32 v34, v110, v34
	v_add_f32_e32 v34, v111, v34
	v_add_f32_e32 v34, v113, v34
	v_add_f32_e32 v34, v114, v34
	v_add_f32_e32 v34, v70, v34
	v_add_f32_e32 v34, v71, v34
	v_add_f32_e32 v34, v72, v34
	v_add_f32_e32 v34, v73, v34
	v_add_f32_e32 v34, v115, v34
	v_add_f32_e32 v34, v66, v34
	v_add_f32_e32 v34, v62, v34
	v_add_f32_e32 v34, v63, v34
	v_add_f32_e32 v34, v64, v34
	v_add_f32_e32 v34, v65, v34
	v_add_f32_e32 v34, v67, v34
	v_add_f32_e32 v34, v68, v34
	v_add_f32_e32 v34, v69, v34
	v_add_f32_e32 v34, v58, v34
	v_add_f32_e32 v34, v59, v34
	v_add_f32_e32 v34, v60, v34
	v_add_f32_e32 v34, v61, v34
	v_add_f32_e32 v34, v54, v34
	v_add_f32_e32 v34, v55, v34
	v_add_f32_e32 v34, v56, v34
	v_add_f32_e32 v34, v57, v34
	v_add_f32_e32 v34, v50, v34
	v_add_f32_e32 v34, v46, v34
	v_add_f32_e32 v34, v47, v34
	v_add_f32_e32 v34, v48, v34
	v_add_f32_e32 v34, v49, v34
	v_add_f32_e32 v1, v34, v1
	s_setprio 0
	ds_bpermute_b32 v36, v190, v1
	v_lshl_add_u64 v[34:35], s[10:11], 0, v[158:159]
	v_lshl_add_u64 v[34:35], v[34:35], 0, v[134:135]
	s_add_i32 s48, s48, s33
	s_cmpk_gt_i32 s48, 0x3ff
	s_waitcnt lgkmcnt(0)
	v_add_f32_e32 v1, v1, v36
	v_div_scale_f32 v36, s[10:11], v1, v1, 1.0
	v_rcp_f32_e32 v37, v36
	v_div_scale_f32 v38, vcc, 1.0, v1, 1.0
	v_fma_f32 v39, -v36, v37, 1.0
	v_fmac_f32_e32 v37, v39, v37
	v_mul_f32_e32 v39, v38, v37
	v_fma_f32 v40, -v36, v39, v38
	v_fmac_f32_e32 v39, v40, v37
	v_fma_f32 v36, -v36, v39, v38
	v_div_fmas_f32 v36, v36, v37, v39
	v_div_fixup_f32 v36, v36, v1, 1.0
	v_pk_mul_f32 v[18:19], v[18:19], v[36:37] op_sel_hi:[1,0]
	v_pk_mul_f32 v[20:21], v[20:21], v[36:37] op_sel_hi:[1,0]
	v_pk_mul_f32 v[2:3], v[2:3], v[36:37] op_sel_hi:[1,0]
	v_pk_mul_f32 v[4:5], v[4:5], v[36:37] op_sel_hi:[1,0]
	v_cvt_pk_bf16_f32 v18, v18, v19
	v_cvt_pk_bf16_f32 v19, v20, v21
	v_cvt_pk_bf16_f32 v2, v2, v3
	v_cvt_pk_bf16_f32 v3, v4, v5
	global_store_dwordx2 v[34:35], v[18:19], off
	v_pk_mul_f32 v[18:19], v[22:23], v[36:37] op_sel_hi:[1,0]
	v_pk_mul_f32 v[20:21], v[24:25], v[36:37] op_sel_hi:[1,0]
	global_store_dwordx2 v[34:35], v[2:3], off offset:64
	v_pk_mul_f32 v[2:3], v[6:7], v[36:37] op_sel_hi:[1,0]
	v_pk_mul_f32 v[4:5], v[8:9], v[36:37] op_sel_hi:[1,0]
	v_cvt_pk_bf16_f32 v18, v18, v19
	v_cvt_pk_bf16_f32 v19, v20, v21
	v_cvt_pk_bf16_f32 v2, v2, v3
	v_cvt_pk_bf16_f32 v3, v4, v5
	global_store_dwordx2 v[34:35], v[18:19], off offset:16
	v_pk_mul_f32 v[18:19], v[26:27], v[36:37] op_sel_hi:[1,0]
	v_pk_mul_f32 v[20:21], v[28:29], v[36:37] op_sel_hi:[1,0]
	global_store_dwordx2 v[34:35], v[2:3], off offset:80
	v_pk_mul_f32 v[2:3], v[10:11], v[36:37] op_sel_hi:[1,0]
	v_pk_mul_f32 v[4:5], v[12:13], v[36:37] op_sel_hi:[1,0]
	v_cvt_pk_bf16_f32 v18, v18, v19
	v_cvt_pk_bf16_f32 v19, v20, v21
	v_cvt_pk_bf16_f32 v2, v2, v3
	v_cvt_pk_bf16_f32 v3, v4, v5
	global_store_dwordx2 v[34:35], v[18:19], off offset:32
	v_pk_mul_f32 v[18:19], v[30:31], v[36:37] op_sel_hi:[1,0]
	v_pk_mul_f32 v[20:21], v[32:33], v[36:37] op_sel_hi:[1,0]
	global_store_dwordx2 v[34:35], v[2:3], off offset:96
	v_pk_mul_f32 v[2:3], v[14:15], v[36:37] op_sel_hi:[1,0]
	v_pk_mul_f32 v[4:5], v[16:17], v[36:37] op_sel_hi:[1,0]
	v_cvt_pk_bf16_f32 v18, v18, v19
	v_cvt_pk_bf16_f32 v19, v20, v21
	v_cvt_pk_bf16_f32 v2, v2, v3
	v_cvt_pk_bf16_f32 v3, v4, v5
	global_store_dwordx2 v[34:35], v[18:19], off offset:48
	global_store_dwordx2 v[34:35], v[2:3], off offset:112
	s_cbranch_scc1 .LBB0_828

.LBB0_821:
	v_mov_b32_e32 v101, v1
	s_waitcnt lgkmcnt(0)
	v_add_f32_e32 v1, v102, v105
	v_fmamk_f32 v1, v1, 0x3c2aaaab, v157
	v_mul_f32_e32 v102, 0x4b800000, v1
	v_cmp_gt_f32_e32 vcc, s41, v1
	v_mov_b32_e32 v123, v133
	v_mov_b32_e32 v109, v103
	v_cndmask_b32_e32 v1, v1, v102, vcc
	v_rsq_f32_e32 v1, v1
	v_mov_b32_e32 v121, v131
	v_mov_b32_e32 v105, v127
	v_mov_b32_e32 v119, v155
	v_mul_f32_e32 v102, 0x45800000, v1
	v_cndmask_b32_e32 v1, v1, v102, vcc
	v_mul_f32_e32 v124, 0x3e16c740, v1
	v_pk_mul_f32 v[102:103], v[124:125], v[122:123] op_sel_hi:[0,1]
	s_waitcnt vmcnt(4)
	v_pk_mul_f32 v[62:63], v[62:63], v[102:103]
	v_mov_b32_e32 v99, v111
	v_cvt_pk_bf16_f32 v102, v62, v63
	v_pk_mul_f32 v[62:63], v[124:125], v[120:121] op_sel_hi:[0,1]
	v_pk_mul_f32 v[62:63], v[64:65], v[62:63]
	v_mov_b32_e32 v111, v181
	v_cvt_pk_bf16_f32 v103, v62, v63
	v_pk_mul_f32 v[62:63], v[124:125], v[104:105] op_sel_hi:[0,1]
	v_pk_mul_f32 v[58:59], v[58:59], v[62:63]
	v_mov_b32_e32 v95, v117
	v_cvt_pk_bf16_f32 v104, v58, v59
	v_pk_mul_f32 v[58:59], v[124:125], v[118:119] op_sel_hi:[0,1]
	v_pk_mul_f32 v[58:59], v[60:61], v[58:59]
	v_mov_b32_e32 v117, v183
	v_cvt_pk_bf16_f32 v105, v58, v59
	v_pk_mul_f32 v[58:59], v[124:125], v[110:111] op_sel_hi:[0,1]
	v_pk_mul_f32 v[54:55], v[54:55], v[58:59]
	v_mov_b32_e32 v107, v113
	v_cvt_pk_bf16_f32 v110, v54, v55
	v_pk_mul_f32 v[54:55], v[124:125], v[116:117] op_sel_hi:[0,1]
	v_mov_b32_e32 v113, v185
	v_pk_mul_f32 v[54:55], v[56:57], v[54:55]
	v_mov_b32_e32 v97, v115
	v_cvt_pk_bf16_f32 v111, v54, v55
	v_pk_mul_f32 v[54:55], v[124:125], v[112:113] op_sel_hi:[0,1]
	v_mov_b32_e32 v115, v187
	v_pk_mul_f32 v[50:51], v[50:51], v[54:55]
	s_lshl_b64 s[38:39], s[12:13], 3
	v_cvt_pk_bf16_f32 v112, v50, v51
	v_pk_mul_f32 v[50:51], v[124:125], v[114:115] op_sel_hi:[0,1]
	v_pk_mul_f32 v[50:51], v[52:53], v[50:51]
	s_or_b32 s0, s38, s49
	v_cvt_pk_bf16_f32 v113, v50, v51
	v_pk_mul_f32 v[50:51], v[124:125], v[98:99] op_sel_hi:[0,1]
	v_pk_mul_f32 v[46:47], v[46:47], v[50:51]
	s_mul_i32 s13, s39, 0xc0
	v_cvt_pk_bf16_f32 v98, v46, v47
	v_pk_mul_f32 v[46:47], v[124:125], v[108:109] op_sel_hi:[0,1]
	v_pk_mul_f32 v[46:47], v[46:47], v[48:49]
	s_mul_hi_u32 s15, s0, 0xc0
	v_cvt_pk_bf16_f32 v99, v46, v47
	v_pk_mul_f32 v[46:47], v[124:125], v[100:101] op_sel_hi:[0,1]
	v_pk_mul_f32 v[42:43], v[46:47], v[42:43]
	v_mov_b32_e32 v93, v125
	v_cvt_pk_bf16_f32 v100, v42, v43
	v_pk_mul_f32 v[42:43], v[124:125], v[106:107] op_sel_hi:[0,1]
	v_pk_mul_f32 v[42:43], v[42:43], v[44:45]
	s_add_i32 s15, s15, s13
	v_cvt_pk_bf16_f32 v101, v42, v43
	v_pk_mul_f32 v[42:43], v[124:125], v[96:97] op_sel_hi:[0,1]
	v_pk_mul_f32 v[38:39], v[42:43], v[38:39]
	s_mulk_i32 s0, 0xc0
	v_cvt_pk_bf16_f32 v106, v38, v39
	v_pk_mul_f32 v[38:39], v[124:125], v[94:95] op_sel_hi:[0,1]
	v_pk_mul_f32 v[38:39], v[38:39], v[40:41]
	s_add_u32 s38, s42, s0
	v_cvt_pk_bf16_f32 v107, v38, v39
	v_pk_mul_f32 v[38:39], v[124:125], v[92:93] op_sel_hi:[0,1]
	v_mov_b32_e32 v91, v179
	v_pk_mul_f32 v[34:35], v[38:39], v[34:35]
	s_addc_u32 s39, s43, s15
	s_lshl_b32 s0, s34, 1
	v_cvt_pk_bf16_f32 v108, v34, v35
	v_pk_mul_f32 v[34:35], v[124:125], v[90:91] op_sel_hi:[0,1]
	s_add_u32 s51, s46, s0
	s_mul_hi_i32 s35, s50, s14
	s_mul_i32 s34, s50, s14
	v_pk_mul_f32 v[34:35], v[34:35], v[36:37]
	s_addc_u32 s52, s47, 0
	s_ashr_i32 s15, s14, 31
	s_lshl_b64 s[34:35], s[34:35], 7
	v_cvt_pk_bf16_f32 v109, v34, v35
	v_pk_mul_f32 v[34:35], v[124:125], v[86:87] op_sel_hi:[0,1]
	v_mov_b32_e32 v36, v10
	v_mov_b32_e32 v37, v15
	s_add_u32 s34, s51, s34
	v_pk_mul_f32 v[54:55], v[34:35], v[36:37]
	v_lshl_add_u64 v[36:37], s[38:39], 0, v[146:147]
	s_addc_u32 s35, s52, s35
	v_pk_mul_f32 v[34:35], v[124:125], v[84:85] op_sel_hi:[0,1]
	v_mov_b32_e32 v15, v11
	v_lshl_add_u64 v[38:39], v[148:149], 1, v[36:37]
	v_lshl_add_u64 v[36:37], s[38:39], 0, v[150:151]
	v_mov_b32_e32 v173, v135
	v_pk_mul_f32 v[10:11], v[34:35], v[14:15]
	v_lshl_add_u64 v[34:35], s[38:39], 0, v[142:143]
	v_lshl_add_u64 v[46:47], v[152:153], 1, v[36:37]
	v_lshl_add_u64 v[50:51], s[34:35], 0, v[172:173]
	v_mad_i64_i32 v[36:37], s[34:35], s50, v154, 0
	v_lshl_add_u64 v[34:35], v[144:145], 1, v[34:35]
	v_lshl_add_u64 v[42:43], v[36:37], 1, v[50:51]
	v_mad_i64_i32 v[52:53], s[34:35], s50, v156, 0
	global_load_dwordx4 v[34:37], v[34:35], off
	s_nop 0
	global_load_dwordx4 v[38:41], v[38:39], off
	s_nop 0
	global_load_dwordx4 v[42:45], v[42:43], off
	s_nop 0
	global_load_dwordx4 v[46:49], v[46:47], off
	v_lshl_add_u64 v[50:51], v[52:53], 1, v[50:51]
	global_load_dwordx4 v[50:53], v[50:51], off
	s_waitcnt vmcnt(5)
	v_mov_b32_e32 v88, v31
	v_mov_b32_e32 v89, v32
	v_mov_b32_e32 v77, v129
	v_mov_b32_e32 v57, v32
	v_mov_b32_e32 v58, v10
	v_mov_b32_e32 v59, v55
	v_mov_b32_e32 v32, v31
	v_mov_b32_e32 v31, v33
	v_mov_b32_e32 v15, v11
	v_mov_b32_e32 v56, v30
	v_pk_mul_f32 v[58:59], v[58:59], v[32:33]
	v_pk_mul_f32 v[10:11], v[10:11], v[30:31]
	v_pk_mul_f32 v[30:31], v[124:125], v[76:77] op_sel_hi:[0,1]
	v_mov_b32_e32 v32, v12
	v_mov_b32_e32 v33, v17
	v_pk_mul_f32 v[30:31], v[30:31], v[32:33]
	v_pk_mul_f32 v[32:33], v[124:125], v[74:75] op_sel_hi:[0,1]
	v_mov_b32_e32 v17, v13
	v_pk_mul_f32 v[12:13], v[32:33], v[16:17]
	v_mov_b32_e32 v82, v27
	v_mov_b32_e32 v83, v28
	v_mov_b32_e32 v73, v175
	v_mov_b32_e32 v14, v54
	v_pk_fma_f32 v[10:11], v[54:55], v[88:89], v[10:11]
	v_mov_b32_e32 v33, v28
	v_mov_b32_e32 v54, v12
	v_mov_b32_e32 v55, v31
	v_mov_b32_e32 v28, v27
	v_mov_b32_e32 v27, v29
	v_mov_b32_e32 v17, v13
	v_mov_b32_e32 v32, v26
	v_pk_mul_f32 v[54:55], v[54:55], v[28:29]
	v_pk_mul_f32 v[12:13], v[12:13], v[26:27]
	v_pk_mul_f32 v[26:27], v[124:125], v[72:73] op_sel_hi:[0,1]
	v_mov_b32_e32 v28, v2
	v_mov_b32_e32 v29, v7
	v_pk_mul_f32 v[26:27], v[26:27], v[28:29]
	v_pk_mul_f32 v[28:29], v[124:125], v[70:71] op_sel_hi:[0,1]
	v_mov_b32_e32 v7, v3
	v_pk_mul_f32 v[2:3], v[28:29], v[6:7]
	v_mov_b32_e32 v80, v23
	v_mov_b32_e32 v81, v24
	v_mov_b32_e32 v69, v177
	v_mov_b32_e32 v16, v30
	v_pk_fma_f32 v[12:13], v[30:31], v[82:83], v[12:13]
	v_mov_b32_e32 v29, v24
	v_mov_b32_e32 v30, v2
	v_mov_b32_e32 v31, v27
	v_mov_b32_e32 v24, v23
	v_mov_b32_e32 v23, v25
	v_mov_b32_e32 v7, v3
	v_mov_b32_e32 v28, v22
	v_pk_mul_f32 v[30:31], v[30:31], v[24:25]
	v_pk_mul_f32 v[2:3], v[2:3], v[22:23]
	v_pk_mul_f32 v[22:23], v[124:125], v[68:69] op_sel_hi:[0,1]
	v_mov_b32_e32 v24, v4
	v_mov_b32_e32 v25, v9
	v_pk_mul_f32 v[22:23], v[22:23], v[24:25]
	v_pk_mul_f32 v[24:25], v[124:125], v[66:67] op_sel_hi:[0,1]
	v_mov_b32_e32 v9, v5
	v_mov_b32_e32 v78, v19
	v_mov_b32_e32 v79, v20
	v_pk_mul_f32 v[4:5], v[24:25], v[8:9]
	v_mov_b32_e32 v25, v20
	v_mov_b32_e32 v20, v19
	v_mov_b32_e32 v19, v21
	v_mov_b32_e32 v6, v26
	v_pk_fma_f32 v[2:3], v[26:27], v[80:81], v[2:3]
	v_mov_b32_e32 v9, v5
	v_mov_b32_e32 v26, v4
	v_pk_mul_f32 v[4:5], v[4:5], v[18:19]
	s_lshl_b64 s[14:15], s[14:15], 7
	v_pk_fma_f32 v[4:5], v[22:23], v[78:79], v[4:5]
	v_cvt_pk_bf16_f32 v116, v2, v3
	v_lshl_add_u64 v[2:3], v[162:163], 0, s[14:15]
	v_cvt_pk_bf16_f32 v117, v4, v5
	v_mad_u64_u32 v[4:5], s[38:39], v2, s50, v[160:161]
	v_mad_i32_i24 v5, v3, s50, v5
	v_lshl_add_u64 v[2:3], v[164:165], 0, s[14:15]
	v_lshl_add_u64 v[174:175], v[4:5], 0, s[0:1]
	v_mad_u64_u32 v[4:5], s[14:15], v2, s50, v[160:161]
	v_mov_b32_e32 v27, v23
	v_mad_i32_i24 v5, v3, s50, v5
	v_mad_i64_i32 v[2:3], s[14:15], s12, v207, v[166:167]
	v_pk_fma_f32 v[16:17], v[16:17], v[32:33], v[54:55] neg_lo:[0,0,1] neg_hi:[0,0,1]
	v_mov_b32_e32 v8, v22
	v_mov_b32_e32 v24, v18
	v_pk_mul_f32 v[26:27], v[26:27], v[20:21]
	v_mad_u64_u32 v[178:179], s[14:15], s49, v206, v[2:3]
	v_mad_i64_i32 v[2:3], s[14:15], s12, v207, v[168:169]
	v_pk_fma_f32 v[14:15], v[14:15], v[56:57], v[58:59] neg_lo:[0,0,1] neg_hi:[0,0,1]
	v_pk_fma_f32 v[6:7], v[6:7], v[28:29], v[30:31] neg_lo:[0,0,1] neg_hi:[0,0,1]
	v_pk_fma_f32 v[8:9], v[8:9], v[24:25], v[26:27] neg_lo:[0,0,1] neg_hi:[0,0,1]
	v_cvt_pk_bf16_f32 v119, v16, v17
	v_add3_u32 v1, v201, v202, s44
	v_mad_u64_u32 v[180:181], s[14:15], s49, v206, v[2:3]
	v_mad_i64_i32 v[2:3], s[14:15], s12, v207, v[170:171]
	v_mov_b32_e32 v16, v135
	v_mov_b32_e32 v17, v135
	v_cvt_pk_bf16_f32 v118, v14, v15
	v_cvt_pk_bf16_f32 v120, v6, v7
	v_cvt_pk_bf16_f32 v121, v8, v9
	v_cvt_pk_bf16_f32 v114, v10, v11
	v_cvt_pk_bf16_f32 v115, v12, v13
	s_waitcnt vmcnt(4)
	ds_write_b128 v193, v[34:37]
	s_waitcnt vmcnt(3)
	ds_write_b128 v196, v[38:41]
	s_waitcnt vmcnt(1)
	ds_write_b128 v199, v[46:49]
	ds_write2_b64 v1, v[42:43], v[44:45] offset1:1
	v_add3_u32 v1, v201, v203, s44
	v_lshl_add_u64 v[176:177], v[4:5], 0, s[0:1]
	v_mad_u64_u32 v[182:183], s[14:15], s49, v206, v[2:3]
	v_mov_b32_e32 v2, v135
	v_mov_b32_e32 v3, v135
	v_mov_b32_e32 v4, v135
	v_mov_b32_e32 v5, v135
	v_mov_b32_e32 v6, v135
	v_mov_b32_e32 v7, v135
	v_mov_b32_e32 v8, v135
	v_mov_b32_e32 v9, v135
	v_mov_b32_e32 v10, v135
	v_mov_b32_e32 v11, v135
	v_mov_b32_e32 v12, v135
	v_mov_b32_e32 v13, v135
	v_mov_b32_e32 v14, v135
	v_mov_b32_e32 v15, v135
	v_mov_b64_e32 v[32:33], v[16:17]
	s_mov_b32 s13, 1
	s_lshr_b32 s34, s50, 7
	s_waitcnt vmcnt(0)
	ds_write2_b64 v1, v[50:51], v[52:53] offset1:1
	v_lshl_add_u64 v[236:237], s[78:79], 0, v[182:183]
	v_lshl_add_u64 v[238:239], s[78:79], 0, v[180:181]
	v_lshl_add_u64 v[240:241], s[78:79], 0, v[178:179]
	global_load_dwordx4 v[224:227], v[236:237], off
	global_load_dwordx4 v[228:231], v[238:239], off
	global_load_dwordx4 v[232:235], v[240:241], off
	v_lshl_add_u64 v[178:179], v[178:179], 0, s[8:9]
	v_lshl_add_u64 v[180:181], v[180:181], 0, s[8:9]
	v_lshl_add_u64 v[182:183], v[182:183], 0, s[8:9]
	v_mov_b32_e32 v133, 0xff800000
	v_mov_b32_e32 v1, 0
	v_mov_b64_e32 v[30:31], v[14:15]
	v_mov_b64_e32 v[28:29], v[12:13]
	v_mov_b64_e32 v[26:27], v[10:11]
	v_mov_b64_e32 v[24:25], v[8:9]
	v_mov_b64_e32 v[22:23], v[6:7]
	v_mov_b64_e32 v[20:21], v[4:5]
	v_mov_b64_e32 v[18:19], v[2:3]
	s_waitcnt lgkmcnt(0)
	s_barrier
	s_cmpk_lt_i32 s40, 0x100
	s_cbranch_scc1 .Lmla_noskew
	s_barrier
.Lmla_noskew:
.LBB0_822:
	s_and_b32 s0, 1, s13
	s_cselect_b32 s12, 0, 0xaa00
	s_cselect_b32 s0, 0xaa00, 0
	s_add_i32 s12, s12, 0
	v_add3_u32 v236, s0, v191, v192
	v_add3_u32 v237, s0, v194, v195
	v_add3_u32 v238, s0, v197, v198
	v_add3_u32 v131, s12, v132, v204
	s_waitcnt vmcnt(0)
	ds_write_b128 v236, v[224:227]
	ds_write_b128 v237, v[228:231]
	ds_write_b128 v238, v[232:235]
	ds_read_b128 v[34:37], v131
	ds_read_b128 v[122:125], v131 offset:32
	s_waitcnt lgkmcnt(1)
	v_mfma_f32_32x32x16_bf16 v[82:97], v[34:37], v[102:105], 0
	ds_read_b128 v[34:37], v131 offset:6656
	ds_read_b128 v[126:129], v131 offset:6688
	s_waitcnt lgkmcnt(1)
	v_mfma_f32_32x32x16_bf16 v[66:81], v[34:37], v[102:105], 0
	ds_read_b128 v[34:37], v131 offset:13312
	ds_read_b128 v[184:187], v131 offset:13344
	s_waitcnt lgkmcnt(1)
	v_mfma_f32_32x32x16_bf16 v[50:65], v[34:37], v[102:105], 0
	ds_read_b128 v[34:37], v131 offset:19968
	ds_read_b128 v[208:211], v131 offset:20000
	v_mfma_f32_32x32x16_bf16 v[82:97], v[122:125], v[110:113], v[82:97]
	s_waitcnt lgkmcnt(1)
	v_mfma_f32_32x32x16_bf16 v[34:49], v[34:37], v[102:105], 0
	v_mfma_f32_32x32x16_bf16 v[66:81], v[126:129], v[110:113], v[66:81]
	ds_read_b128 v[122:125], v131 offset:64
	ds_read_b128 v[126:129], v131 offset:96
	v_mfma_f32_32x32x16_bf16 v[50:65], v[184:187], v[110:113], v[50:65]
	s_waitcnt lgkmcnt(1)
	v_mfma_f32_32x32x16_bf16 v[82:97], v[122:125], v[98:101], v[82:97]
	ds_read_b128 v[122:125], v131 offset:6720
	ds_read_b128 v[184:187], v131 offset:6752
	v_mfma_f32_32x32x16_bf16 v[34:49], v[208:211], v[110:113], v[34:49]
	s_waitcnt lgkmcnt(1)
	v_mfma_f32_32x32x16_bf16 v[66:81], v[122:125], v[98:101], v[66:81]
	ds_read_b128 v[122:125], v131 offset:13376
	ds_read_b128 v[208:211], v131 offset:13408
	s_waitcnt lgkmcnt(1)
	v_mfma_f32_32x32x16_bf16 v[50:65], v[122:125], v[98:101], v[50:65]
	ds_read_b128 v[122:125], v131 offset:20032
	ds_read_b128 v[212:215], v131 offset:20064
	v_mfma_f32_32x32x16_bf16 v[82:97], v[126:129], v[106:109], v[82:97]
	s_waitcnt lgkmcnt(1)
	v_mfma_f32_32x32x16_bf16 v[34:49], v[122:125], v[98:101], v[34:49]
	ds_read_b128 v[122:125], v131 offset:128
	ds_read_b128 v[126:129], v131 offset:160
	v_mfma_f32_32x32x16_bf16 v[66:81], v[184:187], v[106:109], v[66:81]
	s_waitcnt lgkmcnt(1)
	v_mfma_f32_32x32x16_bf16 v[82:97], v[122:125], v[118:121], v[82:97]
	ds_read_b128 v[122:125], v131 offset:6784
	ds_read_b128 v[184:187], v131 offset:6816
	s_waitcnt lgkmcnt(1)
	v_mfma_f32_32x32x16_bf16 v[66:81], v[122:125], v[118:121], v[66:81]
	ds_read_b128 v[122:125], v131 offset:13440
	v_mfma_f32_32x32x16_bf16 v[50:65], v[208:211], v[106:109], v[50:65]
	ds_read_b128 v[208:211], v131 offset:13472
	v_mfma_f32_32x32x16_bf16 v[34:49], v[212:215], v[106:109], v[34:49]
	v_lshl_add_u64 v[212:213], s[78:79], 0, v[174:175]
	v_add_co_u32_e32 v212, vcc, 0xd3d0000, v212
	s_nop 1
	v_addc_co_u32_e32 v213, vcc, 0, v213, vcc
	s_waitcnt lgkmcnt(1)
	v_mfma_f32_32x32x16_bf16 v[50:65], v[122:125], v[118:121], v[50:65]
	v_lshl_add_u64 v[122:123], s[78:79], 0, v[176:177]
	v_add_co_u32_e32 v122, vcc, 0xd3d0000, v122
	s_nop 1
	v_addc_co_u32_e32 v123, vcc, 0, v123, vcc
	v_mfma_f32_32x32x16_bf16 v[82:97], v[126:129], v[114:117], v[82:97]
	global_load_dwordx4 v[126:129], v[212:213], off offset:256
	s_nop 0
	global_load_dwordx4 v[122:125], v[122:123], off offset:256
	ds_read_b128 v[212:215], v131 offset:20096
	ds_read_b128 v[216:219], v131 offset:20128
	s_nop 6
	v_max3_f32 v131, v82, s45, v83
	v_mfma_f32_32x32x16_bf16 v[66:81], v[184:187], v[114:117], v[66:81]
	v_max3_f32 v131, v131, v84, v85
	v_max3_f32 v131, v131, v86, v87
	v_max3_f32 v131, v131, v88, v89
	v_max3_f32 v131, v131, v90, v91
	v_max3_f32 v131, v131, v92, v93
	v_max3_f32 v131, v131, v94, v95
	v_max3_f32 v131, v131, v96, v97
	s_nop 4
	v_max3_f32 v131, v131, v66, v67
	s_waitcnt lgkmcnt(2)
	v_mfma_f32_32x32x16_bf16 v[50:65], v[208:211], v[114:117], v[50:65]
	v_max3_f32 v131, v131, v68, v69
	v_max3_f32 v131, v131, v70, v71
	v_max3_f32 v131, v131, v72, v73
	v_max3_f32 v131, v131, v74, v75
	v_max3_f32 v131, v131, v76, v77
	v_max3_f32 v131, v131, v78, v79
	v_max3_f32 v131, v131, v80, v81
	s_waitcnt lgkmcnt(1)
	v_mfma_f32_32x32x16_bf16 v[34:49], v[212:215], v[118:121], v[34:49]
	s_nop 2
	v_max3_f32 v131, v131, v50, v51
	v_max3_f32 v131, v131, v52, v53
	v_max3_f32 v131, v131, v54, v55
	v_max3_f32 v131, v131, v56, v57
	v_max3_f32 v131, v131, v58, v59
	v_max3_f32 v131, v131, v60, v61
	v_max3_f32 v131, v131, v62, v63
	s_waitcnt lgkmcnt(0)
	v_mfma_f32_32x32x16_bf16 v[34:49], v[216:219], v[114:117], v[34:49]
	v_max3_f32 v131, v131, v64, v65
	s_nop 10
	v_max3_f32 v131, v131, v34, v35
	v_max3_f32 v131, v131, v36, v37
	v_max3_f32 v131, v131, v38, v39
	v_max3_f32 v131, v131, v40, v41
	v_max3_f32 v131, v131, v42, v43
	v_max3_f32 v131, v131, v44, v45
	v_max3_f32 v131, v131, v46, v47
	v_max3_f32 v131, v131, v48, v49
	ds_bpermute_b32 v155, v190, v131
	s_waitcnt lgkmcnt(0)
	v_max3_f32 v131, v133, v131, v155
	v_cmp_gt_f32_e32 vcc, v131, v133
	s_cbranch_vccz .LBB0_824
	v_sub_f32_e32 v133, v133, v131
	v_exp_f32_e32 v184, v133
	s_nop 0
	v_pk_mul_f32 v[32:33], v[32:33], v[184:185] op_sel_hi:[1,0]
	v_pk_mul_f32 v[30:31], v[30:31], v[184:185] op_sel_hi:[1,0]
	v_pk_mul_f32 v[28:29], v[28:29], v[184:185] op_sel_hi:[1,0]
	v_pk_mul_f32 v[26:27], v[26:27], v[184:185] op_sel_hi:[1,0]
	v_pk_mul_f32 v[24:25], v[24:25], v[184:185] op_sel_hi:[1,0]
	v_pk_mul_f32 v[22:23], v[22:23], v[184:185] op_sel_hi:[1,0]
	v_pk_mul_f32 v[20:21], v[20:21], v[184:185] op_sel_hi:[1,0]
	v_pk_mul_f32 v[18:19], v[18:19], v[184:185] op_sel_hi:[1,0]
	v_pk_mul_f32 v[16:17], v[16:17], v[184:185] op_sel_hi:[1,0]
	v_pk_mul_f32 v[14:15], v[14:15], v[184:185] op_sel_hi:[1,0]
	v_pk_mul_f32 v[12:13], v[12:13], v[184:185] op_sel_hi:[1,0]
	v_pk_mul_f32 v[10:11], v[10:11], v[184:185] op_sel_hi:[1,0]
	v_pk_mul_f32 v[8:9], v[8:9], v[184:185] op_sel_hi:[1,0]
	v_pk_mul_f32 v[6:7], v[6:7], v[184:185] op_sel_hi:[1,0]
	v_pk_mul_f32 v[4:5], v[4:5], v[184:185] op_sel_hi:[1,0]
	v_pk_mul_f32 v[2:3], v[2:3], v[184:185] op_sel_hi:[1,0]
	v_mul_f32_e32 v1, v1, v184
.LBB0_824:
	s_barrier
	v_sub_f32_e32 v82, v82, v131
	v_exp_f32_e32 v133, v82
	v_sub_f32_e32 v82, v83, v131
	v_exp_f32_e32 v155, v82
	v_sub_f32_e32 v82, v84, v131
	v_exp_f32_e32 v84, v82
	v_sub_f32_e32 v85, v85, v131
	v_exp_f32_e32 v85, v85
	v_sub_f32_e32 v86, v86, v131
	v_add_f32_e32 v173, 0, v133
	v_exp_f32_e32 v86, v86
	v_sub_f32_e32 v87, v87, v131
	v_add_f32_e32 v173, v155, v173
	v_exp_f32_e32 v87, v87
	v_sub_f32_e32 v88, v88, v131
	v_add_f32_e32 v173, v84, v173
	v_exp_f32_e32 v88, v88
	v_sub_f32_e32 v89, v89, v131
	v_add_f32_e32 v173, v85, v173
	v_exp_f32_e32 v89, v89
	v_sub_f32_e32 v90, v90, v131
	v_add_f32_e32 v173, v86, v173
	v_exp_f32_e32 v90, v90
	v_sub_f32_e32 v91, v91, v131
	v_add_f32_e32 v173, v87, v173
	v_exp_f32_e32 v91, v91
	v_sub_f32_e32 v92, v92, v131
	v_add_f32_e32 v173, v88, v173
	v_exp_f32_e32 v92, v92
	v_sub_f32_e32 v93, v93, v131
	v_add_f32_e32 v173, v89, v173
	v_exp_f32_e32 v93, v93
	v_sub_f32_e32 v94, v94, v131
	v_add_f32_e32 v173, v90, v173
	v_exp_f32_e32 v94, v94
	v_sub_f32_e32 v95, v95, v131
	v_add_f32_e32 v173, v91, v173
	v_exp_f32_e32 v95, v95
	v_sub_f32_e32 v96, v96, v131
	v_add_f32_e32 v173, v92, v173
	v_exp_f32_e32 v96, v96
	v_sub_f32_e32 v97, v97, v131
	v_add_f32_e32 v173, v93, v173
	v_exp_f32_e32 v97, v97
	v_sub_f32_e32 v66, v66, v131
	v_add_f32_e32 v173, v94, v173
	v_exp_f32_e32 v208, v66
	v_sub_f32_e32 v66, v67, v131
	v_add_f32_e32 v173, v95, v173
	v_exp_f32_e32 v209, v66
	v_sub_f32_e32 v66, v68, v131
	v_add_f32_e32 v173, v96, v173
	v_exp_f32_e32 v210, v66
	v_sub_f32_e32 v67, v69, v131
	v_add_f32_e32 v66, v97, v173
	v_exp_f32_e32 v173, v67
	v_sub_f32_e32 v67, v70, v131
	v_add_f32_e32 v66, v208, v66
	v_exp_f32_e32 v211, v67
	v_sub_f32_e32 v67, v71, v131
	v_add_f32_e32 v66, v209, v66
	v_exp_f32_e32 v212, v67
	v_sub_f32_e32 v67, v72, v131
	v_add_f32_e32 v66, v210, v66
	v_exp_f32_e32 v213, v67
	v_sub_f32_e32 v67, v73, v131
	v_add_f32_e32 v66, v173, v66
	v_exp_f32_e32 v214, v67
	v_sub_f32_e32 v67, v74, v131
	v_add_f32_e32 v66, v211, v66
	v_exp_f32_e32 v74, v67
	v_sub_f32_e32 v67, v75, v131
	v_add_f32_e32 v66, v212, v66
	v_exp_f32_e32 v75, v67
	v_sub_f32_e32 v67, v76, v131
	v_add_f32_e32 v66, v213, v66
	v_exp_f32_e32 v76, v67
	v_sub_f32_e32 v67, v77, v131
	v_add_f32_e32 v66, v214, v66
	v_exp_f32_e32 v77, v67
	v_sub_f32_e32 v67, v78, v131
	v_add_f32_e32 v66, v74, v66
	v_exp_f32_e32 v78, v67
	v_sub_f32_e32 v67, v79, v131
	v_add_f32_e32 v66, v75, v66
	v_exp_f32_e32 v79, v67
	v_sub_f32_e32 v67, v80, v131
	v_add_f32_e32 v66, v76, v66
	v_exp_f32_e32 v80, v67
	v_sub_f32_e32 v67, v81, v131
	v_add_f32_e32 v66, v77, v66
	v_exp_f32_e32 v81, v67
	v_sub_f32_e32 v50, v50, v131
	v_add_f32_e32 v66, v78, v66
	v_exp_f32_e32 v215, v50
	v_sub_f32_e32 v50, v51, v131
	v_add_f32_e32 v66, v79, v66
	v_exp_f32_e32 v216, v50
	v_sub_f32_e32 v50, v52, v131
	v_add_f32_e32 v66, v80, v66
	v_exp_f32_e32 v217, v50
	v_add_f32_e32 v50, v81, v66
	v_add_f32_e32 v50, v215, v50
	v_add_f32_e32 v50, v216, v50
	v_add_f32_e32 v218, v217, v50
	v_sub_f32_e32 v50, v53, v131
	v_exp_f32_e32 v219, v50
	v_sub_f32_e32 v50, v54, v131
	v_add3_u32 v54, s12, v189, v205
	v_exp_f32_e32 v220, v50
	v_sub_f32_e32 v50, v55, v131
	v_add_u32_e32 v222, 0x6800, v54
	v_exp_f32_e32 v221, v50
	ds_read2_b64 v[50:53], v222 offset1:2
	v_sub_f32_e32 v55, v56, v131
	v_exp_f32_e32 v223, v55
	v_cvt_pk_bf16_f32 v66, v133, v155
	v_cvt_pk_bf16_f32 v67, v84, v85
	v_cvt_pk_bf16_f32 v68, v86, v87
	v_cvt_pk_bf16_f32 v69, v88, v89
	v_add_u32_e32 v84, 0x8800, v54
	ds_read2_b64 v[70:73], v84 offset0:32 offset1:34
	s_waitcnt lgkmcnt(1)
	v_mfma_f32_32x32x16_bf16 v[18:33], v[50:53], v[66:69], v[18:33]
	v_add_f32_e32 v50, v219, v218
	v_add_f32_e32 v50, v220, v50
	v_add_f32_e32 v50, v221, v50
	v_add_f32_e32 v85, v223, v50
	v_sub_f32_e32 v50, v57, v131
	v_exp_f32_e32 v86, v50
	ds_read2_b64 v[50:53], v222 offset0:4 offset1:6
	v_sub_f32_e32 v54, v58, v131
	s_waitcnt lgkmcnt(1)
	v_mfma_f32_32x32x16_bf16 v[2:17], v[70:73], v[66:69], v[2:17]
	v_exp_f32_e32 v70, v54
	v_cvt_pk_bf16_f32 v54, v90, v91
	v_cvt_pk_bf16_f32 v55, v92, v93
	v_cvt_pk_bf16_f32 v56, v94, v95
	v_cvt_pk_bf16_f32 v57, v96, v97
	ds_read2_b64 v[66:69], v84 offset0:36 offset1:38
	v_sub_f32_e32 v34, v34, v131
	s_waitcnt lgkmcnt(1)
	v_mfma_f32_32x32x16_bf16 v[18:33], v[50:53], v[54:57], v[18:33]
	v_add_f32_e32 v50, v86, v85
	v_add_f32_e32 v71, v70, v50
	v_sub_f32_e32 v50, v59, v131
	v_exp_f32_e32 v72, v50
	v_sub_f32_e32 v50, v60, v131
	v_exp_f32_e32 v73, v50
	ds_read2_b64 v[50:53], v222 offset0:8 offset1:10
	s_waitcnt lgkmcnt(1)
	v_mfma_f32_32x32x16_bf16 v[2:17], v[66:69], v[54:57], v[2:17]
	v_sub_f32_e32 v54, v61, v131
	v_exp_f32_e32 v85, v54
	v_cvt_pk_bf16_f32 v54, v208, v209
	v_cvt_pk_bf16_f32 v55, v210, v173
	v_cvt_pk_bf16_f32 v56, v211, v212
	v_cvt_pk_bf16_f32 v57, v213, v214
	ds_read2_b64 v[58:61], v84 offset0:40 offset1:42
	v_lshl_add_u64 v[186:187], s[78:79], 0, v[182:183]
	s_waitcnt lgkmcnt(1)
	v_mfma_f32_32x32x16_bf16 v[18:33], v[50:53], v[54:57], v[18:33]
	v_sub_f32_e32 v50, v62, v131
	v_exp_f32_e32 v87, v50
	v_sub_f32_e32 v50, v63, v131
	v_exp_f32_e32 v88, v50
	v_sub_f32_e32 v50, v64, v131
	v_exp_f32_e32 v89, v50
	ds_read2_b64 v[50:53], v222 offset0:12 offset1:14
	s_waitcnt lgkmcnt(1)
	v_mfma_f32_32x32x16_bf16 v[2:17], v[58:61], v[54:57], v[2:17]
	v_sub_f32_e32 v54, v65, v131
	v_exp_f32_e32 v90, v54
	v_cvt_pk_bf16_f32 v54, v74, v75
	v_cvt_pk_bf16_f32 v55, v76, v77
	v_cvt_pk_bf16_f32 v56, v78, v79
	v_cvt_pk_bf16_f32 v57, v80, v81
	ds_read2_b64 v[58:61], v84 offset0:44 offset1:46
	v_exp_f32_e32 v74, v34
	s_waitcnt lgkmcnt(1)
	v_mfma_f32_32x32x16_bf16 v[18:33], v[50:53], v[54:57], v[18:33]
	ds_read2_b64 v[50:53], v222 offset0:16 offset1:18
	v_sub_f32_e32 v34, v35, v131
	v_exp_f32_e32 v75, v34
	v_sub_f32_e32 v34, v36, v131
	v_exp_f32_e32 v76, v34
	v_sub_f32_e32 v34, v37, v131
	v_exp_f32_e32 v77, v34
	v_cvt_pk_bf16_f32 v34, v215, v216
	v_cvt_pk_bf16_f32 v35, v217, v219
	v_cvt_pk_bf16_f32 v36, v220, v221
	v_cvt_pk_bf16_f32 v37, v223, v86
	v_lshl_add_u64 v[184:185], s[78:79], 0, v[180:181]
	v_lshl_add_u64 v[82:83], s[78:79], 0, v[178:179]
	s_waitcnt lgkmcnt(0)
	v_mfma_f32_32x32x16_bf16 v[18:33], v[50:53], v[34:37], v[18:33]
	global_load_dwordx4 v[224:227], v[186:187], off
	global_load_dwordx4 v[232:235], v[82:83], off
	v_sub_f32_e32 v38, v38, v131
	v_exp_f32_e32 v78, v38
	v_sub_f32_e32 v38, v39, v131
	v_exp_f32_e32 v79, v38
	v_sub_f32_e32 v38, v40, v131
	v_mfma_f32_32x32x16_bf16 v[2:17], v[58:61], v[54:57], v[2:17]
	global_load_dwordx4 v[228:231], v[184:185], off
	ds_read2_b64 v[54:57], v84 offset0:48 offset1:50
	ds_read2_b64 v[66:69], v222 offset0:20 offset1:22
	v_exp_f32_e32 v80, v38
	v_sub_f32_e32 v42, v42, v131
	s_waitcnt lgkmcnt(1)
	v_mfma_f32_32x32x16_bf16 v[2:17], v[54:57], v[34:37], v[2:17]
	v_sub_f32_e32 v34, v41, v131
	ds_read2_b64 v[38:41], v84 offset0:52 offset1:54
	v_exp_f32_e32 v81, v34
	v_cvt_pk_bf16_f32 v34, v70, v72
	v_cvt_pk_bf16_f32 v35, v73, v85
	v_cvt_pk_bf16_f32 v36, v87, v88
	v_cvt_pk_bf16_f32 v37, v89, v90
	ds_read2_b64 v[54:57], v222 offset0:24 offset1:26
	s_add_i32 s0, s0, 0
	s_waitcnt lgkmcnt(2)
	v_mfma_f32_32x32x16_bf16 v[18:33], v[66:69], v[34:37], v[18:33]
	v_exp_f32_e32 v66, v42
	v_sub_f32_e32 v42, v43, v131
	v_exp_f32_e32 v67, v42
	v_sub_f32_e32 v42, v44, v131
	v_exp_f32_e32 v68, v42
	v_sub_f32_e32 v42, v46, v131
	v_exp_f32_e32 v46, v42
	s_waitcnt lgkmcnt(1)
	v_mfma_f32_32x32x16_bf16 v[2:17], v[38:41], v[34:37], v[2:17]
	ds_read2_b64 v[38:41], v84 offset0:56 offset1:58
	v_sub_f32_e32 v42, v47, v131
	v_sub_f32_e32 v34, v45, v131
	v_exp_f32_e32 v47, v42
	v_sub_f32_e32 v42, v48, v131
	v_exp_f32_e32 v69, v34
	v_cvt_pk_bf16_f32 v34, v74, v75
	v_cvt_pk_bf16_f32 v35, v76, v77
	v_cvt_pk_bf16_f32 v36, v78, v79
	v_cvt_pk_bf16_f32 v37, v80, v81
	v_exp_f32_e32 v48, v42
	ds_read2_b64 v[42:45], v222 offset0:28 offset1:30
	s_waitcnt lgkmcnt(2)
	v_mfma_f32_32x32x16_bf16 v[18:33], v[54:57], v[34:37], v[18:33]
	s_add_i32 s13, s13, 1
	v_lshl_add_u64 v[174:175], v[174:175], 0, s[6:7]
	v_lshl_add_u64 v[176:177], v[176:177], 0, s[6:7]
	v_lshl_add_u64 v[178:179], v[178:179], 0, s[8:9]
	v_lshl_add_u64 v[180:181], v[180:181], 0, s[8:9]
	s_cmp_eq_u32 s34, s13
	v_lshl_add_u64 v[182:183], v[182:183], 0, s[8:9]
	s_waitcnt lgkmcnt(1)
	v_mfma_f32_32x32x16_bf16 v[2:17], v[38:41], v[34:37], v[2:17]
	v_sub_f32_e32 v34, v49, v131
	v_exp_f32_e32 v49, v34
	ds_read2_b64 v[38:41], v84 offset0:60 offset1:62
	v_cvt_pk_bf16_f32 v34, v66, v67
	v_cvt_pk_bf16_f32 v35, v68, v69
	v_cvt_pk_bf16_f32 v36, v46, v47
	v_cvt_pk_bf16_f32 v37, v48, v49
	s_waitcnt lgkmcnt(1)
	s_nop 0
	v_mfma_f32_32x32x16_bf16 v[18:33], v[42:45], v[34:37], v[18:33]
	v_add_f32_e32 v42, v72, v71
	v_add_f32_e32 v42, v73, v42
	v_add_f32_e32 v42, v85, v42
	v_add_f32_e32 v42, v87, v42
	v_add_f32_e32 v42, v88, v42
	v_add_f32_e32 v42, v89, v42
	v_add_f32_e32 v42, v90, v42
	s_waitcnt lgkmcnt(0)
	v_mfma_f32_32x32x16_bf16 v[2:17], v[38:41], v[34:37], v[2:17]
	v_add_f32_e32 v34, v74, v42
	v_add_f32_e32 v34, v75, v34
	v_add_f32_e32 v34, v76, v34
	v_add_f32_e32 v34, v77, v34
	v_add_f32_e32 v34, v78, v34
	v_add_f32_e32 v34, v79, v34
	v_add_f32_e32 v34, v80, v34
	v_add_f32_e32 v34, v81, v34
	v_add_f32_e32 v34, v66, v34
	v_add_f32_e32 v34, v67, v34
	v_add_f32_e32 v34, v68, v34
	v_add_f32_e32 v34, v69, v34
	v_add_f32_e32 v34, v46, v34
	v_add_f32_e32 v34, v47, v34
	v_add_f32_e32 v34, v48, v34
	v_add_f32_e32 v34, v49, v34
	v_add_f32_e32 v1, v34, v1
	v_add_u32_e32 v34, s0, v200
	v_add3_u32 v35, v34, v202, s44
	v_add3_u32 v34, v34, v203, s44
	s_waitcnt vmcnt(3)
	ds_write2_b64 v35, v[126:127], v[128:129] offset1:1
	ds_write2_b64 v34, v[122:123], v[124:125] offset1:1
	s_waitcnt lgkmcnt(0)
	s_barrier
	s_cbranch_scc1 .LBB0_826
	v_mov_b32_e32 v133, v131
	s_branch .LBB0_822
